# v16 plus QKV epilogue sum-of-squares xor-16/32 steps by permlane16/32 swaps instead of ds_bpermute
# baseline (speedup 1.0000x reference)
.LBB0_225:
	v_cndmask_b32_e64 v184, 1.0, v222, s[40:41]
	v_and_b32_e32 v217, 64, v223
	s_waitcnt vmcnt(0)
	v_pk_mul_f32 v[146:147], v[184:185], v[146:147] op_sel_hi:[0,1]
	v_pk_mul_f32 v[144:145], v[184:185], v[144:145] op_sel_hi:[0,1]
	v_pk_mul_f32 v[142:143], v[184:185], v[142:143] op_sel_hi:[0,1]
	v_pk_mul_f32 v[140:141], v[184:185], v[140:141] op_sel_hi:[0,1]
	v_pk_mul_f32 v[138:139], v[184:185], v[138:139] op_sel_hi:[0,1]
	v_pk_mul_f32 v[136:137], v[184:185], v[136:137] op_sel_hi:[0,1]
	v_pk_mul_f32 v[134:135], v[184:185], v[134:135] op_sel_hi:[0,1]
	v_pk_mul_f32 v[132:133], v[184:185], v[132:133] op_sel_hi:[0,1]
	v_xor_b32_e32 v184, 16, v223
	v_add_u32_e32 v218, 64, v217
	v_cmp_lt_i32_e32 vcc, v184, v218
	v_pk_mul_f32 v[232:233], v[128:129], v[128:129]
	s_nop 0
	v_cndmask_b32_e32 v184, v223, v184, vcc
	v_lshlrev_b32_e32 v217, 2, v184
	v_xor_b32_e32 v184, 32, v223
	v_cmp_lt_i32_e32 vcc, v184, v218
	v_pk_mul_f32 v[218:219], v[130:131], v[130:131]
	s_nop 0
	v_pk_mov_b32 v[234:235], v[232:233], v[218:219] op_sel:[1,0]
	v_mov_b32_e32 v233, v219
	v_pk_add_f32 v[218:219], v[234:235], v[232:233]
	v_pk_mul_f32 v[232:233], v[126:127], v[126:127]
	v_pk_mul_f32 v[234:235], v[124:125], v[124:125]
	v_pk_add_f32 v[218:219], v[218:219], v[218:219] op_sel:[0,1] op_sel_hi:[1,0]
	v_pk_mov_b32 v[236:237], v[234:235], v[232:233] op_sel:[1,0]
	v_mov_b32_e32 v235, v233
	v_pk_add_f32 v[232:233], v[236:237], v[234:235]
	v_mul_f32_e32 v234, v116, v116
	v_mul_f32_e32 v235, v117, v117
	v_pk_add_f32 v[232:233], v[232:233], v[232:233] op_sel:[0,1] op_sel_hi:[1,0]
	v_mov_b32_e32 v219, v234
	v_mov_b32_e32 v233, v235
	v_pk_add_f32 v[218:219], v[218:219], v[232:233]
	v_mul_f32_e32 v232, v121, v121
	v_mul_f32_e32 v234, v123, v123
	v_mul_f32_e32 v236, v118, v118
	v_mul_f32_e32 v237, v119, v119
	v_pk_fma_f32 v[232:233], v[120:121], v[120:121], v[232:233] op_sel_hi:[1,1,0]
	v_pk_fma_f32 v[234:235], v[122:123], v[122:123], v[234:235] op_sel_hi:[1,1,0]
	v_mov_b32_e32 v233, v236
	v_mov_b32_e32 v235, v237
	v_pk_add_f32 v[232:233], v[232:233], v[234:235]
	v_cndmask_b32_e32 v184, v223, v184, vcc
	v_pk_add_f32 v[218:219], v[218:219], v[232:233]
	v_lshlrev_b32_e32 v184, 2, v184
	v_add_f32_e32 v218, v218, v219
	v_mov_b32_e32 v219, v218
	s_nop 1
	v_permlane16_swap_b32_e32 v218, v219
	s_andn2_b64 vcc, exec, s[4:5]
	s_nop 1
	v_add_f32_e32 v218, v218, v219
	v_mov_b32_e32 v219, v218
	s_nop 1
	v_permlane32_swap_b32_e32 v218, v219
	s_nop 1
	v_add_f32_e32 v218, v218, v219
	v_fmamk_f32 v218, v218, 0x3c800000, v1
	v_rsq_f32_e32 v218, v218
	s_nop 0
	v_pk_mul_f32 v[116:117], v[116:117], v[218:219] op_sel_hi:[1,0]
	v_pk_mul_f32 v[128:129], v[128:129], v[218:219] op_sel_hi:[1,0]
	v_pk_mul_f32 v[130:131], v[130:131], v[218:219] op_sel_hi:[1,0]
	v_pk_mul_f32 v[232:233], v[124:125], v[218:219] op_sel_hi:[1,0]
	v_pk_mul_f32 v[124:125], v[126:127], v[218:219] op_sel_hi:[1,0]
	v_pk_mul_f32 v[120:121], v[120:121], v[218:219] op_sel_hi:[1,0]
	v_pk_mul_f32 v[122:123], v[122:123], v[218:219] op_sel_hi:[1,0]
	v_pk_mul_f32 v[118:119], v[118:119], v[218:219] op_sel_hi:[1,0]
	v_pk_mul_f32 v[218:219], v[132:133], v[116:117]
	v_cndmask_b32_e64 v116, 0, 1, s[4:5]
	v_pk_mul_f32 v[130:131], v[146:147], v[130:131]
	v_pk_mul_f32 v[128:129], v[144:145], v[128:129]
	v_pk_mul_f32 v[124:125], v[142:143], v[124:125]
	v_pk_mul_f32 v[126:127], v[140:141], v[232:233]
	v_pk_mul_f32 v[122:123], v[138:139], v[122:123]
	v_pk_mul_f32 v[120:121], v[136:137], v[120:121]
	v_pk_mul_f32 v[118:119], v[134:135], v[118:119]
	v_cmp_ne_u32_e64 s[40:41], 1, v116
	s_cbranch_vccnz .LBB0_227
	v_pk_mul_f32 v[232:233], v[208:209], v[126:127]
	v_pk_mul_f32 v[116:117], v[210:211], v[124:125]
	v_pk_fma_f32 v[232:233], v[212:213], v[128:129], v[232:233] neg_lo:[0,0,1] neg_hi:[0,0,1]
	v_pk_mul_f32 v[128:129], v[208:209], v[128:129]
	v_pk_fma_f32 v[234:235], v[214:215], v[130:131], v[116:117] neg_lo:[0,0,1] neg_hi:[0,0,1]
	v_pk_mul_f32 v[116:117], v[210:211], v[130:131]
	v_pk_fma_f32 v[126:127], v[212:213], v[126:127], v[128:129]
	v_pk_mul_f32 v[128:129], v[202:203], v[218:219]
	v_pk_fma_f32 v[124:125], v[214:215], v[124:125], v[116:117]
	v_pk_mul_f32 v[116:117], v[204:205], v[118:119]
	v_pk_fma_f32 v[128:129], v[200:201], v[120:121], v[128:129] neg_lo:[0,0,1] neg_hi:[0,0,1]
	v_pk_mul_f32 v[120:121], v[202:203], v[120:121]
	v_pk_fma_f32 v[130:131], v[206:207], v[122:123], v[116:117] neg_lo:[0,0,1] neg_hi:[0,0,1]
	v_pk_mul_f32 v[116:117], v[204:205], v[122:123]
	v_pk_fma_f32 v[218:219], v[200:201], v[218:219], v[120:121]
	v_mov_b64_e32 v[120:121], v[128:129]
	v_mov_b64_e32 v[122:123], v[130:131]
	v_mov_b64_e32 v[128:129], v[232:233]
	v_pk_fma_f32 v[118:119], v[206:207], v[118:119], v[116:117]
	v_mov_b64_e32 v[130:131], v[234:235]
.LBB0_227:
	s_lshl_b32 s1, s94, 8
	s_or_b32 s1, s1, s65
	s_add_i32 s0, s0, s56
	v_add_u32_e32 v116, s1, v216
	v_add_u32_e32 v216, s0, v231
	v_mad_i64_i32 v[232:233], s[0:1], s50, v216, 0
	v_ashrrev_i32_e32 v117, 31, v116
	v_lshl_add_u64 v[232:233], v[232:233], 1, s[80:81]
	v_lshl_add_u64 v[232:233], v[116:117], 1, v[232:233]
	v_cvt_pk_bf16_f32 v120, v120, v121
	v_cvt_pk_bf16_f32 v121, v122, v123
	global_store_dwordx2 v[232:233], v[120:121], off offset:64
	v_cvt_pk_bf16_f32 v120, v218, v219
	v_cvt_pk_bf16_f32 v121, v118, v119
	global_store_dwordx2 v[232:233], v[120:121], off offset:96
	v_pk_mul_f32 v[118:119], v[114:115], v[114:115]
	v_pk_mul_f32 v[120:121], v[112:113], v[112:113]
	v_cvt_pk_bf16_f32 v126, v126, v127
	v_pk_mov_b32 v[122:123], v[120:121], v[118:119] op_sel:[1,0]
	v_mov_b32_e32 v121, v119
	v_pk_add_f32 v[118:119], v[122:123], v[120:121]
	v_pk_mul_f32 v[120:121], v[110:111], v[110:111]
	v_pk_mul_f32 v[122:123], v[108:109], v[108:109]
	v_cvt_pk_bf16_f32 v127, v124, v125
	v_pk_mov_b32 v[124:125], v[122:123], v[120:121] op_sel:[1,0]
	v_mov_b32_e32 v123, v121
	v_pk_add_f32 v[120:121], v[124:125], v[122:123]
	v_mul_f32_e32 v122, v100, v100
	v_mul_f32_e32 v123, v101, v101
	v_pk_add_f32 v[118:119], v[118:119], v[118:119] op_sel:[0,1] op_sel_hi:[1,0]
	v_pk_add_f32 v[120:121], v[120:121], v[120:121] op_sel:[0,1] op_sel_hi:[1,0]
	v_mov_b32_e32 v119, v122
	v_mov_b32_e32 v121, v123
	v_pk_add_f32 v[118:119], v[118:119], v[120:121]
	v_mul_f32_e32 v120, v105, v105
	v_mul_f32_e32 v122, v107, v107
	v_mul_f32_e32 v124, v102, v102
	v_mul_f32_e32 v125, v103, v103
	v_pk_fma_f32 v[120:121], v[104:105], v[104:105], v[120:121] op_sel_hi:[1,1,0]
	v_pk_fma_f32 v[122:123], v[106:107], v[106:107], v[122:123] op_sel_hi:[1,1,0]
	v_mov_b32_e32 v121, v124
	v_mov_b32_e32 v123, v125
	v_pk_add_f32 v[120:121], v[120:121], v[122:123]
	v_cvt_pk_bf16_f32 v128, v128, v129
	v_pk_add_f32 v[118:119], v[118:119], v[120:121]
	v_cvt_pk_bf16_f32 v129, v130, v131
	v_add_f32_e32 v118, v118, v119
	v_mov_b32_e32 v119, v118
	s_nop 1
	v_permlane16_swap_b32_e32 v118, v119
	s_and_b64 vcc, exec, s[40:41]
	global_store_dwordx2 v[232:233], v[128:129], off
	global_store_dwordx2 v[232:233], v[126:127], off offset:32
	s_nop 1
	v_add_f32_e32 v118, v118, v119
	v_mov_b32_e32 v119, v118
	s_nop 1
	v_permlane32_swap_b32_e32 v118, v119
	s_nop 1
	v_add_f32_e32 v118, v118, v119
	v_fmamk_f32 v118, v118, 0x3c800000, v1
	v_rsq_f32_e32 v118, v118
	s_nop 0
	v_pk_mul_f32 v[120:121], v[108:109], v[118:119] op_sel_hi:[1,0]
	v_pk_mul_f32 v[112:113], v[112:113], v[118:119] op_sel_hi:[1,0]
	v_pk_mul_f32 v[114:115], v[114:115], v[118:119] op_sel_hi:[1,0]
	v_pk_mul_f32 v[108:109], v[110:111], v[118:119] op_sel_hi:[1,0]
	v_pk_mul_f32 v[110:111], v[140:141], v[120:121]
	v_pk_mul_f32 v[104:105], v[104:105], v[118:119] op_sel_hi:[1,0]
	v_pk_mul_f32 v[106:107], v[106:107], v[118:119] op_sel_hi:[1,0]
	v_pk_mul_f32 v[120:121], v[100:101], v[118:119] op_sel_hi:[1,0]
	v_pk_mul_f32 v[100:101], v[102:103], v[118:119] op_sel_hi:[1,0]
	v_pk_mul_f32 v[114:115], v[146:147], v[114:115]
	v_pk_mul_f32 v[112:113], v[144:145], v[112:113]
	v_pk_mul_f32 v[108:109], v[142:143], v[108:109]
	v_pk_mul_f32 v[106:107], v[138:139], v[106:107]
	v_pk_mul_f32 v[104:105], v[136:137], v[104:105]
	v_pk_mul_f32 v[100:101], v[134:135], v[100:101]
	v_pk_mul_f32 v[102:103], v[132:133], v[120:121]
	s_cbranch_vccnz .LBB0_229
	v_pk_mul_f32 v[118:119], v[210:211], v[108:109]
	v_pk_mul_f32 v[122:123], v[208:209], v[110:111]
	v_pk_fma_f32 v[120:121], v[214:215], v[114:115], v[118:119] neg_lo:[0,0,1] neg_hi:[0,0,1]
	v_pk_fma_f32 v[118:119], v[212:213], v[112:113], v[122:123] neg_lo:[0,0,1] neg_hi:[0,0,1]
	v_pk_mul_f32 v[114:115], v[210:211], v[114:115]
	v_pk_mul_f32 v[112:113], v[208:209], v[112:113]
	v_pk_fma_f32 v[108:109], v[214:215], v[108:109], v[114:115]
	v_pk_fma_f32 v[110:111], v[212:213], v[110:111], v[112:113]
	v_pk_mul_f32 v[114:115], v[194:195], v[100:101]
	v_pk_mul_f32 v[112:113], v[192:193], v[102:103]
	v_pk_fma_f32 v[114:115], v[198:199], v[106:107], v[114:115] neg_lo:[0,0,1] neg_hi:[0,0,1]
	v_pk_fma_f32 v[112:113], v[196:197], v[104:105], v[112:113] neg_lo:[0,0,1] neg_hi:[0,0,1]
	v_pk_mul_f32 v[106:107], v[194:195], v[106:107]
	v_pk_mul_f32 v[104:105], v[192:193], v[104:105]
	v_pk_fma_f32 v[100:101], v[198:199], v[100:101], v[106:107]
	v_pk_fma_f32 v[102:103], v[196:197], v[102:103], v[104:105]
	v_mov_b64_e32 v[104:105], v[112:113]
	v_mov_b64_e32 v[106:107], v[114:115]
	v_mov_b64_e32 v[112:113], v[118:119]
	v_mov_b64_e32 v[114:115], v[120:121]
.LBB0_229:
	v_add_u32_e32 v118, 16, v216
	v_mad_i64_i32 v[118:119], s[0:1], s50, v118, 0
	v_lshl_add_u64 v[118:119], v[118:119], 1, s[80:81]
	v_lshl_add_u64 v[118:119], v[116:117], 1, v[118:119]
	v_cvt_pk_bf16_f32 v102, v102, v103
	v_cvt_pk_bf16_f32 v103, v100, v101
	v_cvt_pk_bf16_f32 v104, v104, v105
	v_cvt_pk_bf16_f32 v105, v106, v107
	global_store_dwordx2 v[118:119], v[102:103], off offset:96
	v_pk_mul_f32 v[100:101], v[98:99], v[98:99]
	v_pk_mul_f32 v[102:103], v[96:97], v[96:97]
	global_store_dwordx2 v[118:119], v[104:105], off offset:64
	v_pk_mov_b32 v[104:105], v[102:103], v[100:101] op_sel:[1,0]
	v_mov_b32_e32 v103, v101
	v_pk_add_f32 v[100:101], v[104:105], v[102:103]
	v_pk_mul_f32 v[102:103], v[94:95], v[94:95]
	v_pk_mul_f32 v[104:105], v[92:93], v[92:93]
	v_pk_add_f32 v[100:101], v[100:101], v[100:101] op_sel:[0,1] op_sel_hi:[1,0]
	v_pk_mov_b32 v[106:107], v[104:105], v[102:103] op_sel:[1,0]
	v_mov_b32_e32 v105, v103
	v_pk_add_f32 v[102:103], v[106:107], v[104:105]
	v_mul_f32_e32 v104, v84, v84
	v_mul_f32_e32 v105, v85, v85
	v_pk_add_f32 v[102:103], v[102:103], v[102:103] op_sel:[0,1] op_sel_hi:[1,0]
	v_mov_b32_e32 v101, v104
	v_mov_b32_e32 v103, v105
	v_pk_add_f32 v[100:101], v[100:101], v[102:103]
	v_mul_f32_e32 v102, v89, v89
	v_mul_f32_e32 v104, v91, v91
	v_mul_f32_e32 v106, v86, v86
	v_mul_f32_e32 v107, v87, v87
	v_pk_fma_f32 v[102:103], v[88:89], v[88:89], v[102:103] op_sel_hi:[1,1,0]
	v_pk_fma_f32 v[104:105], v[90:91], v[90:91], v[104:105] op_sel_hi:[1,1,0]
	v_mov_b32_e32 v103, v106
	v_mov_b32_e32 v105, v107
	v_pk_add_f32 v[102:103], v[102:103], v[104:105]
	v_cvt_pk_bf16_f32 v112, v112, v113
	v_pk_add_f32 v[100:101], v[100:101], v[102:103]
	v_cvt_pk_bf16_f32 v113, v114, v115
	v_add_f32_e32 v100, v100, v101
	v_mov_b32_e32 v101, v100
	s_nop 1
	v_permlane16_swap_b32_e32 v100, v101
	v_cvt_pk_bf16_f32 v110, v110, v111
	v_cvt_pk_bf16_f32 v111, v108, v109
	s_and_b64 vcc, exec, s[40:41]
	global_store_dwordx2 v[118:119], v[112:113], off
	s_nop 1
	v_add_f32_e32 v100, v100, v101
	v_mov_b32_e32 v101, v100
	s_nop 1
	v_permlane32_swap_b32_e32 v100, v101
	global_store_dwordx2 v[118:119], v[110:111], off offset:32
	s_nop 1
	v_add_f32_e32 v100, v100, v101
	v_fmamk_f32 v100, v100, 0x3c800000, v1
	v_rsq_f32_e32 v100, v100
	s_nop 0
	v_pk_mul_f32 v[102:103], v[92:93], v[100:101] op_sel_hi:[1,0]
	v_pk_mul_f32 v[96:97], v[96:97], v[100:101] op_sel_hi:[1,0]
	v_pk_mul_f32 v[98:99], v[98:99], v[100:101] op_sel_hi:[1,0]
	v_pk_mul_f32 v[92:93], v[94:95], v[100:101] op_sel_hi:[1,0]
	v_pk_mul_f32 v[94:95], v[140:141], v[102:103]
	v_pk_mul_f32 v[88:89], v[88:89], v[100:101] op_sel_hi:[1,0]
	v_pk_mul_f32 v[90:91], v[90:91], v[100:101] op_sel_hi:[1,0]
	v_pk_mul_f32 v[102:103], v[84:85], v[100:101] op_sel_hi:[1,0]
	v_pk_mul_f32 v[84:85], v[86:87], v[100:101] op_sel_hi:[1,0]
	v_pk_mul_f32 v[98:99], v[146:147], v[98:99]
	v_pk_mul_f32 v[96:97], v[144:145], v[96:97]
	v_pk_mul_f32 v[92:93], v[142:143], v[92:93]
	v_pk_mul_f32 v[90:91], v[138:139], v[90:91]
	v_pk_mul_f32 v[88:89], v[136:137], v[88:89]
	v_pk_mul_f32 v[84:85], v[134:135], v[84:85]
	v_pk_mul_f32 v[86:87], v[132:133], v[102:103]
	s_cbranch_vccnz .LBB0_231
	v_pk_mul_f32 v[100:101], v[210:211], v[92:93]
	v_pk_mul_f32 v[104:105], v[208:209], v[94:95]
	v_pk_fma_f32 v[102:103], v[214:215], v[98:99], v[100:101] neg_lo:[0,0,1] neg_hi:[0,0,1]
	v_pk_fma_f32 v[100:101], v[212:213], v[96:97], v[104:105] neg_lo:[0,0,1] neg_hi:[0,0,1]
	v_pk_mul_f32 v[98:99], v[210:211], v[98:99]
	v_pk_mul_f32 v[96:97], v[208:209], v[96:97]
	v_pk_fma_f32 v[92:93], v[214:215], v[92:93], v[98:99]
	v_pk_fma_f32 v[94:95], v[212:213], v[94:95], v[96:97]
	v_pk_mul_f32 v[98:99], v[176:177], v[84:85]
	v_pk_mul_f32 v[96:97], v[174:175], v[86:87]
	v_pk_fma_f32 v[98:99], v[190:191], v[90:91], v[98:99] neg_lo:[0,0,1] neg_hi:[0,0,1]
	v_pk_fma_f32 v[96:97], v[178:179], v[88:89], v[96:97] neg_lo:[0,0,1] neg_hi:[0,0,1]
	v_pk_mul_f32 v[90:91], v[176:177], v[90:91]
	v_pk_mul_f32 v[88:89], v[174:175], v[88:89]
	v_pk_fma_f32 v[84:85], v[190:191], v[84:85], v[90:91]
	v_pk_fma_f32 v[86:87], v[178:179], v[86:87], v[88:89]
	v_mov_b64_e32 v[88:89], v[96:97]
	v_mov_b64_e32 v[90:91], v[98:99]
	v_mov_b64_e32 v[96:97], v[100:101]
	v_mov_b64_e32 v[98:99], v[102:103]
.LBB0_231:
	v_add_u32_e32 v100, 32, v216
	v_mad_i64_i32 v[100:101], s[0:1], s50, v100, 0
	v_lshl_add_u64 v[100:101], v[100:101], 1, s[80:81]
	v_lshl_add_u64 v[100:101], v[116:117], 1, v[100:101]
	v_cvt_pk_bf16_f32 v86, v86, v87
	v_cvt_pk_bf16_f32 v87, v84, v85
	v_cvt_pk_bf16_f32 v88, v88, v89
	v_cvt_pk_bf16_f32 v89, v90, v91
	global_store_dwordx2 v[100:101], v[86:87], off offset:96
	v_pk_mul_f32 v[84:85], v[82:83], v[82:83]
	v_pk_mul_f32 v[86:87], v[80:81], v[80:81]
	global_store_dwordx2 v[100:101], v[88:89], off offset:64
	v_pk_mov_b32 v[88:89], v[86:87], v[84:85] op_sel:[1,0]
	v_mov_b32_e32 v87, v85
	v_pk_add_f32 v[84:85], v[88:89], v[86:87]
	v_pk_mul_f32 v[86:87], v[78:79], v[78:79]
	v_pk_mul_f32 v[88:89], v[76:77], v[76:77]
	v_pk_add_f32 v[84:85], v[84:85], v[84:85] op_sel:[0,1] op_sel_hi:[1,0]
	v_pk_mov_b32 v[90:91], v[88:89], v[86:87] op_sel:[1,0]
	v_mov_b32_e32 v89, v87
	v_pk_add_f32 v[86:87], v[90:91], v[88:89]
	v_mul_f32_e32 v88, v68, v68
	v_mul_f32_e32 v89, v69, v69
	v_pk_add_f32 v[86:87], v[86:87], v[86:87] op_sel:[0,1] op_sel_hi:[1,0]
	v_mov_b32_e32 v85, v88
	v_mov_b32_e32 v87, v89
	v_pk_add_f32 v[84:85], v[84:85], v[86:87]
	v_mul_f32_e32 v86, v73, v73
	v_mul_f32_e32 v88, v75, v75
	v_mul_f32_e32 v90, v70, v70
	v_mul_f32_e32 v91, v71, v71
	v_pk_fma_f32 v[86:87], v[72:73], v[72:73], v[86:87] op_sel_hi:[1,1,0]
	v_pk_fma_f32 v[88:89], v[74:75], v[74:75], v[88:89] op_sel_hi:[1,1,0]
	v_mov_b32_e32 v87, v90
	v_mov_b32_e32 v89, v91
	v_pk_add_f32 v[86:87], v[86:87], v[88:89]
	v_cvt_pk_bf16_f32 v96, v96, v97
	v_pk_add_f32 v[84:85], v[84:85], v[86:87]
	v_cvt_pk_bf16_f32 v97, v98, v99
	v_add_f32_e32 v84, v84, v85
	v_mov_b32_e32 v85, v84
	s_nop 1
	v_permlane16_swap_b32_e32 v84, v85
	v_cvt_pk_bf16_f32 v94, v94, v95
	v_cvt_pk_bf16_f32 v95, v92, v93
	s_and_b64 vcc, exec, s[40:41]
	global_store_dwordx2 v[100:101], v[96:97], off
	s_nop 1
	v_add_f32_e32 v84, v84, v85
	v_mov_b32_e32 v85, v84
	s_nop 1
	v_permlane32_swap_b32_e32 v84, v85
	global_store_dwordx2 v[100:101], v[94:95], off offset:32
	s_nop 1
	v_add_f32_e32 v84, v84, v85
	v_fmamk_f32 v84, v84, 0x3c800000, v1
	v_rsq_f32_e32 v84, v84
	s_nop 0
	v_pk_mul_f32 v[86:87], v[76:77], v[84:85] op_sel_hi:[1,0]
	v_pk_mul_f32 v[80:81], v[80:81], v[84:85] op_sel_hi:[1,0]
	v_pk_mul_f32 v[82:83], v[82:83], v[84:85] op_sel_hi:[1,0]
	v_pk_mul_f32 v[76:77], v[78:79], v[84:85] op_sel_hi:[1,0]
	v_pk_mul_f32 v[78:79], v[140:141], v[86:87]
	v_pk_mul_f32 v[72:73], v[72:73], v[84:85] op_sel_hi:[1,0]
	v_pk_mul_f32 v[74:75], v[74:75], v[84:85] op_sel_hi:[1,0]
	v_pk_mul_f32 v[86:87], v[68:69], v[84:85] op_sel_hi:[1,0]
	v_pk_mul_f32 v[68:69], v[70:71], v[84:85] op_sel_hi:[1,0]
	v_pk_mul_f32 v[82:83], v[146:147], v[82:83]
	v_pk_mul_f32 v[80:81], v[144:145], v[80:81]
	v_pk_mul_f32 v[76:77], v[142:143], v[76:77]
	v_pk_mul_f32 v[74:75], v[138:139], v[74:75]
	v_pk_mul_f32 v[72:73], v[136:137], v[72:73]
	v_pk_mul_f32 v[68:69], v[134:135], v[68:69]
	v_pk_mul_f32 v[70:71], v[132:133], v[86:87]
	s_cbranch_vccnz .LBB0_233
	v_pk_mul_f32 v[84:85], v[210:211], v[76:77]
	v_pk_mul_f32 v[88:89], v[208:209], v[78:79]
	v_pk_fma_f32 v[86:87], v[214:215], v[82:83], v[84:85] neg_lo:[0,0,1] neg_hi:[0,0,1]
	v_pk_fma_f32 v[84:85], v[212:213], v[80:81], v[88:89] neg_lo:[0,0,1] neg_hi:[0,0,1]
	v_pk_mul_f32 v[82:83], v[210:211], v[82:83]
	v_pk_mul_f32 v[80:81], v[208:209], v[80:81]
	v_pk_fma_f32 v[76:77], v[214:215], v[76:77], v[82:83]
	v_pk_fma_f32 v[78:79], v[212:213], v[78:79], v[80:81]
	v_pk_mul_f32 v[82:83], v[168:169], v[68:69]
	v_pk_mul_f32 v[80:81], v[164:165], v[70:71]
	v_pk_fma_f32 v[82:83], v[172:173], v[74:75], v[82:83] neg_lo:[0,0,1] neg_hi:[0,0,1]
	v_pk_fma_f32 v[80:81], v[170:171], v[72:73], v[80:81] neg_lo:[0,0,1] neg_hi:[0,0,1]
	v_pk_mul_f32 v[74:75], v[168:169], v[74:75]
	v_pk_mul_f32 v[72:73], v[164:165], v[72:73]
	v_pk_fma_f32 v[68:69], v[172:173], v[68:69], v[74:75]
	v_pk_fma_f32 v[70:71], v[170:171], v[70:71], v[72:73]
	v_mov_b64_e32 v[72:73], v[80:81]
	v_mov_b64_e32 v[74:75], v[82:83]
	v_mov_b64_e32 v[80:81], v[84:85]
	v_mov_b64_e32 v[82:83], v[86:87]
.LBB0_233:
	v_add_u32_e32 v84, 48, v216
	v_mad_i64_i32 v[84:85], s[0:1], s50, v84, 0
	v_lshl_add_u64 v[84:85], v[84:85], 1, s[80:81]
	v_lshl_add_u64 v[84:85], v[116:117], 1, v[84:85]
	v_cvt_pk_bf16_f32 v70, v70, v71
	v_cvt_pk_bf16_f32 v71, v68, v69
	v_cvt_pk_bf16_f32 v72, v72, v73
	v_cvt_pk_bf16_f32 v73, v74, v75
	global_store_dwordx2 v[84:85], v[70:71], off offset:96
	v_pk_mul_f32 v[68:69], v[64:65], v[64:65]
	v_pk_mul_f32 v[70:71], v[62:63], v[62:63]
	global_store_dwordx2 v[84:85], v[72:73], off offset:64
	v_pk_mov_b32 v[72:73], v[70:71], v[68:69] op_sel:[1,0]
	v_mov_b32_e32 v71, v69
	v_pk_add_f32 v[68:69], v[72:73], v[70:71]
	v_pk_mul_f32 v[70:71], v[60:61], v[60:61]
	v_pk_mul_f32 v[72:73], v[58:59], v[58:59]
	v_pk_add_f32 v[68:69], v[68:69], v[68:69] op_sel:[0,1] op_sel_hi:[1,0]
	v_pk_mov_b32 v[74:75], v[72:73], v[70:71] op_sel:[1,0]
	v_mov_b32_e32 v73, v71
	v_pk_add_f32 v[70:71], v[74:75], v[72:73]
	v_mul_f32_e32 v72, v50, v50
	v_mul_f32_e32 v73, v51, v51
	v_pk_add_f32 v[70:71], v[70:71], v[70:71] op_sel:[0,1] op_sel_hi:[1,0]
	v_mov_b32_e32 v69, v72
	v_mov_b32_e32 v71, v73
	v_pk_add_f32 v[68:69], v[68:69], v[70:71]
	v_mul_f32_e32 v70, v55, v55
	v_mul_f32_e32 v72, v57, v57
	v_mul_f32_e32 v74, v52, v52
	v_mul_f32_e32 v75, v53, v53
	v_pk_fma_f32 v[70:71], v[54:55], v[54:55], v[70:71] op_sel_hi:[1,1,0]
	v_pk_fma_f32 v[72:73], v[56:57], v[56:57], v[72:73] op_sel_hi:[1,1,0]
	v_mov_b32_e32 v71, v74
	v_mov_b32_e32 v73, v75
	v_pk_add_f32 v[70:71], v[70:71], v[72:73]
	v_cvt_pk_bf16_f32 v80, v80, v81
	v_pk_add_f32 v[68:69], v[68:69], v[70:71]
	v_cvt_pk_bf16_f32 v81, v82, v83
	v_add_f32_e32 v68, v68, v69
	v_mov_b32_e32 v69, v68
	s_nop 1
	v_permlane16_swap_b32_e32 v68, v69
	v_cvt_pk_bf16_f32 v78, v78, v79
	v_cvt_pk_bf16_f32 v79, v76, v77
	s_and_b64 vcc, exec, s[40:41]
	global_store_dwordx2 v[84:85], v[80:81], off
	s_nop 1
	v_add_f32_e32 v68, v68, v69
	v_mov_b32_e32 v69, v68
	s_nop 1
	v_permlane32_swap_b32_e32 v68, v69
	global_store_dwordx2 v[84:85], v[78:79], off offset:32
	s_nop 1
	v_add_f32_e32 v68, v68, v69
	v_fmamk_f32 v68, v68, 0x3c800000, v1
	v_rsq_f32_e32 v68, v68
	s_nop 0
	v_pk_mul_f32 v[70:71], v[58:59], v[68:69] op_sel_hi:[1,0]
	v_pk_mul_f32 v[62:63], v[62:63], v[68:69] op_sel_hi:[1,0]
	v_pk_mul_f32 v[64:65], v[64:65], v[68:69] op_sel_hi:[1,0]
	v_pk_mul_f32 v[58:59], v[60:61], v[68:69] op_sel_hi:[1,0]
	v_pk_mul_f32 v[60:61], v[140:141], v[70:71]
	v_pk_mul_f32 v[54:55], v[54:55], v[68:69] op_sel_hi:[1,0]
	v_pk_mul_f32 v[56:57], v[56:57], v[68:69] op_sel_hi:[1,0]
	v_pk_mul_f32 v[70:71], v[50:51], v[68:69] op_sel_hi:[1,0]
	v_pk_mul_f32 v[50:51], v[52:53], v[68:69] op_sel_hi:[1,0]
	v_pk_mul_f32 v[64:65], v[146:147], v[64:65]
	v_pk_mul_f32 v[62:63], v[144:145], v[62:63]
	v_pk_mul_f32 v[58:59], v[142:143], v[58:59]
	v_pk_mul_f32 v[56:57], v[138:139], v[56:57]
	v_pk_mul_f32 v[54:55], v[136:137], v[54:55]
	v_pk_mul_f32 v[50:51], v[134:135], v[50:51]
	v_pk_mul_f32 v[52:53], v[132:133], v[70:71]
	s_cbranch_vccnz .LBB0_235
	v_pk_mul_f32 v[68:69], v[160:161], v[58:59]
	v_pk_mul_f32 v[72:73], v[158:159], v[60:61]
	v_pk_fma_f32 v[70:71], v[166:167], v[64:65], v[68:69] neg_lo:[0,0,1] neg_hi:[0,0,1]
	v_pk_fma_f32 v[68:69], v[162:163], v[62:63], v[72:73] neg_lo:[0,0,1] neg_hi:[0,0,1]
	v_pk_mul_f32 v[62:63], v[158:159], v[62:63]
	v_pk_mul_f32 v[64:65], v[160:161], v[64:65]
	v_pk_fma_f32 v[60:61], v[162:163], v[60:61], v[62:63]
	v_pk_mul_f32 v[62:63], v[204:205], v[50:51]
	v_pk_mul_f32 v[72:73], v[202:203], v[52:53]
	v_pk_fma_f32 v[58:59], v[166:167], v[58:59], v[64:65]
	v_pk_fma_f32 v[64:65], v[206:207], v[56:57], v[62:63] neg_lo:[0,0,1] neg_hi:[0,0,1]
	v_pk_fma_f32 v[62:63], v[200:201], v[54:55], v[72:73] neg_lo:[0,0,1] neg_hi:[0,0,1]
	v_pk_mul_f32 v[56:57], v[204:205], v[56:57]
	v_pk_mul_f32 v[54:55], v[202:203], v[54:55]
	v_pk_fma_f32 v[50:51], v[206:207], v[50:51], v[56:57]
	v_pk_fma_f32 v[52:53], v[200:201], v[52:53], v[54:55]
	v_mov_b64_e32 v[54:55], v[62:63]
	v_mov_b64_e32 v[56:57], v[64:65]
	v_mov_b64_e32 v[62:63], v[68:69]
	v_mov_b64_e32 v[64:65], v[70:71]
.LBB0_235:
	v_add_u32_e32 v68, 0x80, v216
	v_mad_i64_i32 v[68:69], s[0:1], s50, v68, 0
	v_lshl_add_u64 v[68:69], v[68:69], 1, s[80:81]
	v_lshl_add_u64 v[68:69], v[116:117], 1, v[68:69]
	v_cvt_pk_bf16_f32 v52, v52, v53
	v_cvt_pk_bf16_f32 v53, v50, v51
	v_cvt_pk_bf16_f32 v54, v54, v55
	v_cvt_pk_bf16_f32 v55, v56, v57
	global_store_dwordx2 v[68:69], v[52:53], off offset:96
	v_pk_mul_f32 v[50:51], v[48:49], v[48:49]
	v_pk_mul_f32 v[52:53], v[46:47], v[46:47]
	global_store_dwordx2 v[68:69], v[54:55], off offset:64
	v_pk_mov_b32 v[54:55], v[52:53], v[50:51] op_sel:[1,0]
	v_mov_b32_e32 v53, v51
	v_pk_add_f32 v[50:51], v[54:55], v[52:53]
	v_pk_mul_f32 v[52:53], v[44:45], v[44:45]
	v_pk_mul_f32 v[54:55], v[42:43], v[42:43]
	v_pk_add_f32 v[50:51], v[50:51], v[50:51] op_sel:[0,1] op_sel_hi:[1,0]
	v_pk_mov_b32 v[56:57], v[54:55], v[52:53] op_sel:[1,0]
	v_mov_b32_e32 v55, v53
	v_pk_add_f32 v[52:53], v[56:57], v[54:55]
	v_mul_f32_e32 v54, v34, v34
	v_mul_f32_e32 v55, v35, v35
	v_pk_add_f32 v[52:53], v[52:53], v[52:53] op_sel:[0,1] op_sel_hi:[1,0]
	v_mov_b32_e32 v51, v54
	v_mov_b32_e32 v53, v55
	v_pk_add_f32 v[50:51], v[50:51], v[52:53]
	v_mul_f32_e32 v52, v39, v39
	v_mul_f32_e32 v54, v41, v41
	v_mul_f32_e32 v56, v36, v36
	v_mul_f32_e32 v57, v37, v37
	v_pk_fma_f32 v[52:53], v[38:39], v[38:39], v[52:53] op_sel_hi:[1,1,0]
	v_pk_fma_f32 v[54:55], v[40:41], v[40:41], v[54:55] op_sel_hi:[1,1,0]
	v_mov_b32_e32 v53, v56
	v_mov_b32_e32 v55, v57
	v_pk_add_f32 v[52:53], v[52:53], v[54:55]
	v_cvt_pk_bf16_f32 v62, v62, v63
	v_pk_add_f32 v[50:51], v[50:51], v[52:53]
	v_cvt_pk_bf16_f32 v63, v64, v65
	v_add_f32_e32 v50, v50, v51
	v_mov_b32_e32 v51, v50
	s_nop 1
	v_permlane16_swap_b32_e32 v50, v51
	v_cvt_pk_bf16_f32 v60, v60, v61
	v_cvt_pk_bf16_f32 v61, v58, v59
	s_and_b64 vcc, exec, s[40:41]
	global_store_dwordx2 v[68:69], v[62:63], off
	s_nop 1
	v_add_f32_e32 v50, v50, v51
	v_mov_b32_e32 v51, v50
	s_nop 1
	v_permlane32_swap_b32_e32 v50, v51
	global_store_dwordx2 v[68:69], v[60:61], off offset:32
	s_nop 1
	v_add_f32_e32 v50, v50, v51
	v_fmamk_f32 v50, v50, 0x3c800000, v1
	v_rsq_f32_e32 v50, v50
	s_nop 0
	v_pk_mul_f32 v[52:53], v[42:43], v[50:51] op_sel_hi:[1,0]
	v_pk_mul_f32 v[46:47], v[46:47], v[50:51] op_sel_hi:[1,0]
	v_pk_mul_f32 v[48:49], v[48:49], v[50:51] op_sel_hi:[1,0]
	v_pk_mul_f32 v[42:43], v[44:45], v[50:51] op_sel_hi:[1,0]
	v_pk_mul_f32 v[44:45], v[140:141], v[52:53]
	v_pk_mul_f32 v[38:39], v[38:39], v[50:51] op_sel_hi:[1,0]
	v_pk_mul_f32 v[40:41], v[40:41], v[50:51] op_sel_hi:[1,0]
	v_pk_mul_f32 v[52:53], v[34:35], v[50:51] op_sel_hi:[1,0]
	v_pk_mul_f32 v[34:35], v[36:37], v[50:51] op_sel_hi:[1,0]
	v_pk_mul_f32 v[48:49], v[146:147], v[48:49]
	v_pk_mul_f32 v[46:47], v[144:145], v[46:47]
	v_pk_mul_f32 v[42:43], v[142:143], v[42:43]
	v_pk_mul_f32 v[40:41], v[138:139], v[40:41]
	v_pk_mul_f32 v[38:39], v[136:137], v[38:39]
	v_pk_mul_f32 v[34:35], v[134:135], v[34:35]
	v_pk_mul_f32 v[36:37], v[132:133], v[52:53]
	s_cbranch_vccnz .LBB0_237
	v_pk_mul_f32 v[50:51], v[160:161], v[42:43]
	v_pk_mul_f32 v[54:55], v[158:159], v[44:45]
	v_pk_fma_f32 v[52:53], v[166:167], v[48:49], v[50:51] neg_lo:[0,0,1] neg_hi:[0,0,1]
	v_pk_fma_f32 v[50:51], v[162:163], v[46:47], v[54:55] neg_lo:[0,0,1] neg_hi:[0,0,1]
	v_pk_mul_f32 v[48:49], v[160:161], v[48:49]
	v_pk_mul_f32 v[46:47], v[158:159], v[46:47]
	v_pk_fma_f32 v[42:43], v[166:167], v[42:43], v[48:49]
	v_pk_fma_f32 v[44:45], v[162:163], v[44:45], v[46:47]
	v_pk_mul_f32 v[48:49], v[194:195], v[34:35]
	v_pk_mul_f32 v[46:47], v[192:193], v[36:37]
	v_pk_fma_f32 v[48:49], v[198:199], v[40:41], v[48:49] neg_lo:[0,0,1] neg_hi:[0,0,1]
	v_pk_fma_f32 v[46:47], v[196:197], v[38:39], v[46:47] neg_lo:[0,0,1] neg_hi:[0,0,1]
	v_pk_mul_f32 v[40:41], v[194:195], v[40:41]
	v_pk_mul_f32 v[38:39], v[192:193], v[38:39]
	v_pk_fma_f32 v[34:35], v[198:199], v[34:35], v[40:41]
	v_pk_fma_f32 v[36:37], v[196:197], v[36:37], v[38:39]
	v_mov_b64_e32 v[38:39], v[46:47]
	v_mov_b64_e32 v[40:41], v[48:49]
	v_mov_b64_e32 v[46:47], v[50:51]
	v_mov_b64_e32 v[48:49], v[52:53]
.LBB0_237:
	v_add_u32_e32 v50, 0x90, v216
	v_mad_i64_i32 v[50:51], s[0:1], s50, v50, 0
	v_lshl_add_u64 v[50:51], v[50:51], 1, s[80:81]
	v_lshl_add_u64 v[50:51], v[116:117], 1, v[50:51]
	v_cvt_pk_bf16_f32 v36, v36, v37
	v_cvt_pk_bf16_f32 v37, v34, v35
	v_cvt_pk_bf16_f32 v38, v38, v39
	v_cvt_pk_bf16_f32 v39, v40, v41
	global_store_dwordx2 v[50:51], v[36:37], off offset:96
	v_pk_mul_f32 v[34:35], v[32:33], v[32:33]
	v_pk_mul_f32 v[36:37], v[30:31], v[30:31]
	global_store_dwordx2 v[50:51], v[38:39], off offset:64
	v_pk_mov_b32 v[38:39], v[36:37], v[34:35] op_sel:[1,0]
	v_mov_b32_e32 v37, v35
	v_pk_add_f32 v[34:35], v[38:39], v[36:37]
	v_pk_mul_f32 v[36:37], v[28:29], v[28:29]
	v_pk_mul_f32 v[38:39], v[26:27], v[26:27]
	v_pk_add_f32 v[34:35], v[34:35], v[34:35] op_sel:[0,1] op_sel_hi:[1,0]
	v_pk_mov_b32 v[40:41], v[38:39], v[36:37] op_sel:[1,0]
	v_mov_b32_e32 v39, v37
	v_pk_add_f32 v[36:37], v[40:41], v[38:39]
	v_mul_f32_e32 v38, v18, v18
	v_mul_f32_e32 v39, v19, v19
	v_pk_add_f32 v[36:37], v[36:37], v[36:37] op_sel:[0,1] op_sel_hi:[1,0]
	v_mov_b32_e32 v35, v38
	v_mov_b32_e32 v37, v39
	v_pk_add_f32 v[34:35], v[34:35], v[36:37]
	v_mul_f32_e32 v36, v23, v23
	v_mul_f32_e32 v38, v25, v25
	v_mul_f32_e32 v40, v20, v20
	v_mul_f32_e32 v41, v21, v21
	v_pk_fma_f32 v[36:37], v[22:23], v[22:23], v[36:37] op_sel_hi:[1,1,0]
	v_pk_fma_f32 v[38:39], v[24:25], v[24:25], v[38:39] op_sel_hi:[1,1,0]
	v_mov_b32_e32 v37, v40
	v_mov_b32_e32 v39, v41
	v_pk_add_f32 v[36:37], v[36:37], v[38:39]
	v_cvt_pk_bf16_f32 v46, v46, v47
	v_pk_add_f32 v[34:35], v[34:35], v[36:37]
	v_cvt_pk_bf16_f32 v47, v48, v49
	v_add_f32_e32 v34, v34, v35
	v_mov_b32_e32 v35, v34
	s_nop 1
	v_permlane16_swap_b32_e32 v34, v35
	v_cvt_pk_bf16_f32 v44, v44, v45
	v_cvt_pk_bf16_f32 v45, v42, v43
	s_and_b64 vcc, exec, s[40:41]
	global_store_dwordx2 v[50:51], v[46:47], off
	s_nop 1
	v_add_f32_e32 v34, v34, v35
	v_mov_b32_e32 v35, v34
	s_nop 1
	v_permlane32_swap_b32_e32 v34, v35
	global_store_dwordx2 v[50:51], v[44:45], off offset:32
	s_nop 1
	v_add_f32_e32 v34, v34, v35
	v_fmamk_f32 v34, v34, 0x3c800000, v1
	v_rsq_f32_e32 v34, v34
	s_nop 0
	v_pk_mul_f32 v[36:37], v[26:27], v[34:35] op_sel_hi:[1,0]
	v_pk_mul_f32 v[30:31], v[30:31], v[34:35] op_sel_hi:[1,0]
	v_pk_mul_f32 v[32:33], v[32:33], v[34:35] op_sel_hi:[1,0]
	v_pk_mul_f32 v[26:27], v[28:29], v[34:35] op_sel_hi:[1,0]
	v_pk_mul_f32 v[28:29], v[140:141], v[36:37]
	v_pk_mul_f32 v[22:23], v[22:23], v[34:35] op_sel_hi:[1,0]
	v_pk_mul_f32 v[24:25], v[24:25], v[34:35] op_sel_hi:[1,0]
	v_pk_mul_f32 v[36:37], v[18:19], v[34:35] op_sel_hi:[1,0]
	v_pk_mul_f32 v[18:19], v[20:21], v[34:35] op_sel_hi:[1,0]
	v_pk_mul_f32 v[32:33], v[146:147], v[32:33]
	v_pk_mul_f32 v[30:31], v[144:145], v[30:31]
	v_pk_mul_f32 v[26:27], v[142:143], v[26:27]
	v_pk_mul_f32 v[24:25], v[138:139], v[24:25]
	v_pk_mul_f32 v[22:23], v[136:137], v[22:23]
	v_pk_mul_f32 v[18:19], v[134:135], v[18:19]
	v_pk_mul_f32 v[20:21], v[132:133], v[36:37]
	s_cbranch_vccnz .LBB0_239
	v_pk_mul_f32 v[34:35], v[160:161], v[26:27]
	v_pk_mul_f32 v[38:39], v[158:159], v[28:29]
	v_pk_fma_f32 v[36:37], v[166:167], v[32:33], v[34:35] neg_lo:[0,0,1] neg_hi:[0,0,1]
	v_pk_fma_f32 v[34:35], v[162:163], v[30:31], v[38:39] neg_lo:[0,0,1] neg_hi:[0,0,1]
	v_pk_mul_f32 v[32:33], v[160:161], v[32:33]
	v_pk_mul_f32 v[30:31], v[158:159], v[30:31]
	v_pk_fma_f32 v[26:27], v[166:167], v[26:27], v[32:33]
	v_pk_fma_f32 v[28:29], v[162:163], v[28:29], v[30:31]
	v_pk_mul_f32 v[32:33], v[176:177], v[18:19]
	v_pk_mul_f32 v[30:31], v[174:175], v[20:21]
	v_pk_fma_f32 v[32:33], v[190:191], v[24:25], v[32:33] neg_lo:[0,0,1] neg_hi:[0,0,1]
	v_pk_fma_f32 v[30:31], v[178:179], v[22:23], v[30:31] neg_lo:[0,0,1] neg_hi:[0,0,1]
	v_pk_mul_f32 v[24:25], v[176:177], v[24:25]
	v_pk_mul_f32 v[22:23], v[174:175], v[22:23]
	v_pk_fma_f32 v[18:19], v[190:191], v[18:19], v[24:25]
	v_pk_fma_f32 v[20:21], v[178:179], v[20:21], v[22:23]
	v_mov_b64_e32 v[22:23], v[30:31]
	v_mov_b64_e32 v[24:25], v[32:33]
	v_mov_b64_e32 v[30:31], v[34:35]
	v_mov_b64_e32 v[32:33], v[36:37]
.LBB0_239:
	v_add_u32_e32 v34, 0xa0, v216
	v_mad_i64_i32 v[34:35], s[0:1], s50, v34, 0
	v_lshl_add_u64 v[34:35], v[34:35], 1, s[80:81]
	v_lshl_add_u64 v[34:35], v[116:117], 1, v[34:35]
	v_cvt_pk_bf16_f32 v20, v20, v21
	v_cvt_pk_bf16_f32 v21, v18, v19
	v_cvt_pk_bf16_f32 v22, v22, v23
	v_cvt_pk_bf16_f32 v23, v24, v25
	global_store_dwordx2 v[34:35], v[20:21], off offset:96
	v_pk_mul_f32 v[18:19], v[16:17], v[16:17]
	v_pk_mul_f32 v[20:21], v[14:15], v[14:15]
	global_store_dwordx2 v[34:35], v[22:23], off offset:64
	v_pk_mov_b32 v[22:23], v[20:21], v[18:19] op_sel:[1,0]
	v_mov_b32_e32 v21, v19
	v_pk_add_f32 v[18:19], v[22:23], v[20:21]
	v_pk_mul_f32 v[20:21], v[12:13], v[12:13]
	v_pk_mul_f32 v[22:23], v[10:11], v[10:11]
	v_pk_add_f32 v[18:19], v[18:19], v[18:19] op_sel:[0,1] op_sel_hi:[1,0]
	v_pk_mov_b32 v[24:25], v[22:23], v[20:21] op_sel:[1,0]
	v_mov_b32_e32 v23, v21
	v_pk_add_f32 v[20:21], v[24:25], v[22:23]
	v_mul_f32_e32 v22, v2, v2
	v_mul_f32_e32 v23, v3, v3
	v_pk_add_f32 v[20:21], v[20:21], v[20:21] op_sel:[0,1] op_sel_hi:[1,0]
	v_mov_b32_e32 v19, v22
	v_mov_b32_e32 v21, v23
	v_pk_add_f32 v[18:19], v[18:19], v[20:21]
	v_mul_f32_e32 v20, v7, v7
	v_mul_f32_e32 v22, v9, v9
	v_mul_f32_e32 v24, v4, v4
	v_mul_f32_e32 v25, v5, v5
	v_pk_fma_f32 v[20:21], v[6:7], v[6:7], v[20:21] op_sel_hi:[1,1,0]
	v_pk_fma_f32 v[22:23], v[8:9], v[8:9], v[22:23] op_sel_hi:[1,1,0]
	v_mov_b32_e32 v21, v24
	v_mov_b32_e32 v23, v25
	v_pk_add_f32 v[20:21], v[20:21], v[22:23]
	v_cvt_pk_bf16_f32 v30, v30, v31
	v_pk_add_f32 v[18:19], v[18:19], v[20:21]
	v_cvt_pk_bf16_f32 v31, v32, v33
	v_add_f32_e32 v18, v18, v19
	v_mov_b32_e32 v19, v18
	s_nop 1
	v_permlane16_swap_b32_e32 v18, v19
	v_cvt_pk_bf16_f32 v28, v28, v29
	v_cvt_pk_bf16_f32 v29, v26, v27
	s_and_b64 vcc, exec, s[40:41]
	global_store_dwordx2 v[34:35], v[30:31], off
	s_nop 1
	v_add_f32_e32 v18, v18, v19
	v_mov_b32_e32 v19, v18
	s_nop 1
	v_permlane32_swap_b32_e32 v18, v19
	global_store_dwordx2 v[34:35], v[28:29], off offset:32
	s_nop 1
	v_add_f32_e32 v18, v18, v19
	v_fmamk_f32 v18, v18, 0x3c800000, v1
	v_rsq_f32_e32 v18, v18
	s_nop 0
	v_pk_mul_f32 v[20:21], v[10:11], v[18:19] op_sel_hi:[1,0]
	v_pk_mul_f32 v[14:15], v[14:15], v[18:19] op_sel_hi:[1,0]
	v_pk_mul_f32 v[16:17], v[16:17], v[18:19] op_sel_hi:[1,0]
	v_pk_mul_f32 v[10:11], v[12:13], v[18:19] op_sel_hi:[1,0]
	v_pk_mul_f32 v[12:13], v[140:141], v[20:21]
	v_pk_mul_f32 v[6:7], v[6:7], v[18:19] op_sel_hi:[1,0]
	v_pk_mul_f32 v[8:9], v[8:9], v[18:19] op_sel_hi:[1,0]
	v_pk_mul_f32 v[20:21], v[2:3], v[18:19] op_sel_hi:[1,0]
	v_pk_mul_f32 v[2:3], v[4:5], v[18:19] op_sel_hi:[1,0]
	v_pk_mul_f32 v[16:17], v[146:147], v[16:17]
	v_pk_mul_f32 v[14:15], v[144:145], v[14:15]
	v_pk_mul_f32 v[10:11], v[142:143], v[10:11]
	v_pk_mul_f32 v[8:9], v[138:139], v[8:9]
	v_pk_mul_f32 v[6:7], v[136:137], v[6:7]
	v_pk_mul_f32 v[2:3], v[134:135], v[2:3]
	v_pk_mul_f32 v[4:5], v[132:133], v[20:21]
	s_cbranch_vccnz .LBB0_241
	v_pk_mul_f32 v[18:19], v[160:161], v[10:11]
	v_pk_mul_f32 v[22:23], v[158:159], v[12:13]
	v_pk_fma_f32 v[20:21], v[166:167], v[16:17], v[18:19] neg_lo:[0,0,1] neg_hi:[0,0,1]
	v_pk_fma_f32 v[18:19], v[162:163], v[14:15], v[22:23] neg_lo:[0,0,1] neg_hi:[0,0,1]
	v_pk_mul_f32 v[16:17], v[160:161], v[16:17]
	v_pk_mul_f32 v[14:15], v[158:159], v[14:15]
	v_pk_fma_f32 v[10:11], v[166:167], v[10:11], v[16:17]
	v_pk_fma_f32 v[12:13], v[162:163], v[12:13], v[14:15]
	v_pk_mul_f32 v[16:17], v[168:169], v[2:3]
	v_pk_mul_f32 v[14:15], v[164:165], v[4:5]
	v_pk_fma_f32 v[16:17], v[172:173], v[8:9], v[16:17] neg_lo:[0,0,1] neg_hi:[0,0,1]
	v_pk_fma_f32 v[14:15], v[170:171], v[6:7], v[14:15] neg_lo:[0,0,1] neg_hi:[0,0,1]
	v_pk_mul_f32 v[8:9], v[168:169], v[8:9]
	v_pk_mul_f32 v[6:7], v[164:165], v[6:7]
	v_pk_fma_f32 v[2:3], v[172:173], v[2:3], v[8:9]
	v_pk_fma_f32 v[4:5], v[170:171], v[4:5], v[6:7]
	v_mov_b64_e32 v[6:7], v[14:15]
	v_mov_b64_e32 v[8:9], v[16:17]
	v_mov_b64_e32 v[14:15], v[18:19]
	v_mov_b64_e32 v[16:17], v[20:21]
